# v26 + loop back-edge rotation in the diff and MLA KV loops (carried v_mov hoisted above the loop-back barrier, single taken branch)
# baseline (speedup 1.0000x reference)
; #define SBAR() __builtin_amdgcn_sched_barrier(0)
; template <int D0> DEVI void pv_one(f32x16& od, int vb, bf16x8 pa0, bf16x8 pa1, bf16x8 pa2, bf16x8 pa3) {
;   const s16x4 l0 = tr_read<v_rd_off(D0, 0, 0)>(vb), h0 = tr_read<v_rd_off(D0, 0, 1)>(vb), l1 = tr_read<v_rd_off(D0, 1, 0)>(vb), h1 = tr_read<v_rd_off(D0, 1, 1)>(vb);
;   const s16x4 l2 = tr_read<v_rd_off(D0, 2, 0)>(vb), h2 = tr_read<v_rd_off(D0, 2, 1)>(vb), l3 = tr_read<v_rd_off(D0, 3, 0)>(vb), h3 = tr_read<v_rd_off(D0, 3, 1)>(vb);
;   asm volatile("s_waitcnt lgkmcnt(0)" ::: "memory"); SBAR();
; DEVI void partialSM(f32x16& p0, f32x16& p1, float& m_reg, float& mn, float& alpha, float scale) {
;     ...
;   const float mnC = -mn * C;
; #pragma unroll
;   for (int r = 0; r < 16; ++r) p0[r] = fmaf(p0[r], C, mnC);
; #pragma unroll
;   for (int r = 0; r < 16; ++r) p1[r] = fmaf(p1[r], C, mnC);
; #pragma unroll
;   for (int r = 0; r < 16; ++r) p0[r] = __builtin_amdgcn_exp2f(p0[r]);
; }
; DEVI void finishSM(f32x16& p0, f32x16& p1, float alpha, float& l_reg, bf16x8& pa0, bf16x8& pa1, bf16x8& pa2, bf16x8& pa3) {
; #pragma unroll
;   for (int r = 0; r < 16; ++r) p1[r] = __builtin_amdgcn_exp2f(p1[r]);
;   float ps = 0;
; #pragma unroll
;   for (int r = 0; r < 16; ++r) ps += p0[r];
; #pragma unroll
;   for (int r = 0; r < 16; ++r) ps += p1[r];
;   { auto rr = __builtin_amdgcn_permlane32_swap(__float_as_uint(ps), __float_as_uint(ps), false, false);
;     ps = __uint_as_float(rr[0]) + __uint_as_float(rr[1]); }
;   l_reg = l_reg * alpha + ps;
;   PK4(p0, 0, pa0); PK4(p0, 8, pa1); PK4(p1, 0, pa2); PK4(p1, 8, pa3);
.LBB0_417:
	v_cndmask_b32_e64 v174, v176, v174, s[8:9]
	v_mul_f32_e32 v176, 0xbdd53b94, v174
	v_fmamk_f32 v80, v80, 0x3dd53b94, v176
	v_fmamk_f32 v81, v81, 0x3dd53b94, v176
	v_fmamk_f32 v82, v82, 0x3dd53b94, v176
	v_fmamk_f32 v83, v83, 0x3dd53b94, v176
	v_fmamk_f32 v84, v84, 0x3dd53b94, v176
	v_fmamk_f32 v85, v85, 0x3dd53b94, v176
	v_fmamk_f32 v86, v86, 0x3dd53b94, v176
	v_fmamk_f32 v87, v87, 0x3dd53b94, v176
	v_fmamk_f32 v88, v88, 0x3dd53b94, v176
	v_fmamk_f32 v89, v89, 0x3dd53b94, v176
	v_fmamk_f32 v90, v90, 0x3dd53b94, v176
	v_fmamk_f32 v91, v91, 0x3dd53b94, v176
	v_fmamk_f32 v92, v92, 0x3dd53b94, v176
	v_fmamk_f32 v93, v93, 0x3dd53b94, v176
	v_fmamk_f32 v94, v94, 0x3dd53b94, v176
	v_fmamk_f32 v95, v95, 0x3dd53b94, v176
	v_fmamk_f32 v64, v64, 0x3dd53b94, v176
	v_fmamk_f32 v65, v65, 0x3dd53b94, v176
	v_fmamk_f32 v66, v66, 0x3dd53b94, v176
	v_fmamk_f32 v67, v67, 0x3dd53b94, v176
	v_fmamk_f32 v68, v68, 0x3dd53b94, v176
	v_fmamk_f32 v69, v69, 0x3dd53b94, v176
	v_fmamk_f32 v70, v70, 0x3dd53b94, v176
	v_fmamk_f32 v71, v71, 0x3dd53b94, v176
	v_fmamk_f32 v72, v72, 0x3dd53b94, v176
	v_fmamk_f32 v73, v73, 0x3dd53b94, v176
	v_fmamk_f32 v74, v74, 0x3dd53b94, v176
	v_fmamk_f32 v75, v75, 0x3dd53b94, v176
	v_fmamk_f32 v76, v76, 0x3dd53b94, v176
	v_fmamk_f32 v77, v77, 0x3dd53b94, v176
	v_fmamk_f32 v78, v78, 0x3dd53b94, v176
	v_fmac_f32_e32 v176, 0x3dd53b94, v79
	v_exp_f32_e32 v79, v80
	v_exp_f32_e32 v80, v81
	v_exp_f32_e32 v81, v82
	v_exp_f32_e32 v82, v83
	v_exp_f32_e32 v83, v84
	v_exp_f32_e32 v84, v85
	v_exp_f32_e32 v85, v86
	v_exp_f32_e32 v86, v87
	v_exp_f32_e32 v87, v88
	v_exp_f32_e32 v88, v89
	v_exp_f32_e32 v89, v90
	v_exp_f32_e32 v90, v91
	v_exp_f32_e32 v91, v92
	v_exp_f32_e32 v92, v93
	v_exp_f32_e32 v93, v94
	v_exp_f32_e32 v94, v95
	v_exp_f32_e32 v95, v64
	v_add_f32_e32 v64, 0, v79
	v_add_f32_e32 v64, v80, v64
	v_add_f32_e32 v64, v81, v64
	v_add_f32_e32 v64, v82, v64
	v_add_f32_e32 v64, v83, v64
	v_add_f32_e32 v64, v84, v64
	v_add_f32_e32 v64, v85, v64
	v_add_f32_e32 v64, v86, v64
	v_add_f32_e32 v64, v87, v64
	v_add_f32_e32 v64, v88, v64
	v_add_f32_e32 v64, v89, v64
	v_add_f32_e32 v64, v90, v64
	v_add_f32_e32 v64, v91, v64
	v_exp_f32_e32 v197, v65
	v_add_f32_e32 v64, v92, v64
	v_exp_f32_e32 v198, v66
	v_add_f32_e32 v64, v93, v64
	v_exp_f32_e32 v199, v67
	v_add_f32_e32 v64, v94, v64
	v_exp_f32_e32 v200, v68
	v_add_f32_e32 v64, v95, v64
	v_exp_f32_e32 v201, v69
	v_add_f32_e32 v64, v197, v64
	v_exp_f32_e32 v202, v70
	v_add_f32_e32 v64, v198, v64
	v_exp_f32_e32 v203, v71
	v_add_f32_e32 v64, v199, v64
	v_exp_f32_e32 v204, v72
	v_add_f32_e32 v64, v200, v64
	v_exp_f32_e32 v205, v73
	v_add_f32_e32 v64, v201, v64
	v_exp_f32_e32 v206, v74
	v_add_f32_e32 v64, v202, v64
	v_exp_f32_e32 v207, v75
	v_add_f32_e32 v64, v203, v64
	v_exp_f32_e32 v216, v76
	v_add_f32_e32 v64, v204, v64
	v_exp_f32_e32 v217, v77
	v_add_f32_e32 v64, v205, v64
	v_exp_f32_e32 v218, v78
	v_add_f32_e32 v64, v206, v64
	v_exp_f32_e32 v219, v176
	v_add_f32_e32 v64, v207, v64
	v_add_f32_e32 v64, v216, v64
	v_add_f32_e32 v64, v217, v64
	v_add_f32_e32 v64, v218, v64
	v_add_f32_e32 v64, v219, v64
	v_mov_b32_e32 v65, v64
	s_nop 1
	v_permlane32_swap_b32_e32 v64, v65
	v_add_f32_e32 v176, v64, v65
	s_add_i32 s14, s14, 1
	v_fmac_f32_e32 v176, v195, v196
	v_cvt_pk_bf16_f32 v64, v79, v80
	v_cvt_pk_bf16_f32 v65, v81, v82
	v_cvt_pk_bf16_f32 v66, v83, v84
	v_cvt_pk_bf16_f32 v67, v85, v86
	v_cvt_pk_bf16_f32 v68, v87, v88
	v_cvt_pk_bf16_f32 v69, v89, v90
	v_cvt_pk_bf16_f32 v70, v91, v92
	v_cvt_pk_bf16_f32 v71, v93, v94
	v_cvt_pk_bf16_f32 v72, v95, v197
	v_cvt_pk_bf16_f32 v73, v198, v199
	v_cvt_pk_bf16_f32 v74, v200, v201
	v_cvt_pk_bf16_f32 v75, v202, v203
	v_cvt_pk_bf16_f32 v76, v204, v205
	v_cvt_pk_bf16_f32 v77, v206, v207
	v_cvt_pk_bf16_f32 v78, v216, v217
	v_cvt_pk_bf16_f32 v79, v218, v219
	v_permlane32_swap_b32_e32 v64, v66
	v_permlane32_swap_b32_e32 v65, v67
	v_permlane32_swap_b32_e32 v68, v70
	v_permlane32_swap_b32_e32 v69, v71
	v_permlane32_swap_b32_e32 v72, v74
	v_permlane32_swap_b32_e32 v73, v75
	v_permlane32_swap_b32_e32 v76, v78
	v_permlane32_swap_b32_e32 v77, v79
	v_lshl_add_u32 v195, s15, 14, v173
	ds_read_b64_tr_b16 v[80:81], v195 offset:0
	ds_read_b64_tr_b16 v[82:83], v195 offset:0x800
	ds_read_b64_tr_b16 v[84:85], v195 offset:0x1000
	ds_read_b64_tr_b16 v[86:87], v195 offset:0x1800
	ds_read_b64_tr_b16 v[88:89], v195 offset:0x2000
	ds_read_b64_tr_b16 v[90:91], v195 offset:0x2800
	ds_read_b64_tr_b16 v[92:93], v195 offset:0x3000
	ds_read_b64_tr_b16 v[94:95], v195 offset:0x3800
	s_waitcnt lgkmcnt(0)
; #define SBAR() __builtin_amdgcn_sched_barrier(0)
; #define SLOAD(k0) do { vs0 = *(const bf16x8*)(vp0 + (long)(k0) * ldv); vs1 = *(const bf16x8*)(vp0 + (long)((k0) + 32) * ldv); \
;     ksg[0] = *(const bf16x8*)(kp0 + (long)(k0) * ldk0); \
;     if constexpr (DQK == 192) { ksg[1] = *(const bf16x8*)(kp0 + (long)((k0) + 32) * ldk0); ksg[2] = *(const bf16x8*)(kp2 + (long)(k0) * ldk1); } } while (0)
; #define SWAIT() asm volatile("s_waitcnt vmcnt(0)" ::: "memory")
; template <int D0> DEVI void pv_one(f32x16& od, int vb, bf16x8 pa0, bf16x8 pa1, bf16x8 pa2, bf16x8 pa3) {
;   const s16x4 l0 = tr_read<v_rd_off(D0, 0, 0)>(vb), h0 = tr_read<v_rd_off(D0, 0, 1)>(vb), l1 = tr_read<v_rd_off(D0, 1, 0)>(vb), h1 = tr_read<v_rd_off(D0, 1, 1)>(vb);
;   const s16x4 l2 = tr_read<v_rd_off(D0, 2, 0)>(vb), h2 = tr_read<v_rd_off(D0, 2, 1)>(vb), l3 = tr_read<v_rd_off(D0, 3, 0)>(vb), h3 = tr_read<v_rd_off(D0, 3, 1)>(vb);
;   asm volatile("s_waitcnt lgkmcnt(0)" ::: "memory"); SBAR();
;     ...
;   od = __builtin_amdgcn_mfma_f32_32x32x16_bf16(pa0, PK(l0, h0), od, 0, 0, 0);
;   od = __builtin_amdgcn_mfma_f32_32x32x16_bf16(pa1, PK(l1, h1), od, 0, 0, 0);
;   od = __builtin_amdgcn_mfma_f32_32x32x16_bf16(pa2, PK(l2, h2), od, 0, 0, 0);
;   od = __builtin_amdgcn_mfma_f32_32x32x16_bf16(pa3, PK(l3, h3), od, 0, 0, 0);
;     ...
; }
; DEVI void pv_d0(f32x16* o, int vb, bf16x8 pa0, bf16x8 pa1, bf16x8 pa2, bf16x8 pa3) {
;   pv_one<0>(o[0], vb, pa0, pa1, pa2, pa3); pv_one<1>(o[1], vb, pa0, pa1, pa2, pa3); pv_one<2>(o[2], vb, pa0, pa1, pa2, pa3); pv_one<3>(o[3], vb, pa0, pa1, pa2, pa3);
; template <int DQK, bool PIPE>
; DEVI void attn_body(const u16* __restrict__ Qb, int ldq, const u16* __restrict__ K0, int ldk0, const u16* __restrict__ K1, int ldk1,
;                     const u16* __restrict__ Vh, int ldv, u16* __restrict__ Ob, int ldo, int seq, float scale, char* lds) {
;     ...
;     for (int j = 0; j < NT; ++j) {
;       const int bsel = j & 1;
;       if (j + 1 < NT) SLOAD((j + 1) * 64);
;       SBAR(); QKT(p0, p1, K_lds + bsel * SHM_K);
;       partialSM(p0, p1, m_reg, mn, al, scale);
;       RESC(al);
;       finishSM(p0, p1, al, l_reg, pa0, pa1, pa2, pa3); SBAR();
;       pv_d0(o, vb0 + bsel * SHM_V, pa0, pa1, pa2, pa3);
;       if (j + 1 < NT) { SWAIT(); SWRITE(bsel ^ 1); }
;       __syncthreads();
	s_nop 0
	v_mfma_f32_32x32x16_bf16 v[0:15], v[64:67], v[80:83], v[0:15]
	ds_read_b64_tr_b16 v[80:81], v195 offset:0x200
	ds_read_b64_tr_b16 v[82:83], v195 offset:0xa00
	v_mfma_f32_32x32x16_bf16 v[0:15], v[68:71], v[84:87], v[0:15]
	ds_read_b64_tr_b16 v[84:85], v195 offset:0x1200
	ds_read_b64_tr_b16 v[86:87], v195 offset:0x1a00
	v_mfma_f32_32x32x16_bf16 v[0:15], v[72:75], v[88:91], v[0:15]
	ds_read_b64_tr_b16 v[88:89], v195 offset:0x2200
	ds_read_b64_tr_b16 v[90:91], v195 offset:0x2a00
	v_mfma_f32_32x32x16_bf16 v[0:15], v[76:79], v[92:95], v[0:15]
	ds_read_b64_tr_b16 v[92:93], v195 offset:0x3200
	ds_read_b64_tr_b16 v[94:95], v195 offset:0x3a00
	s_waitcnt lgkmcnt(0)
	v_mfma_f32_32x32x16_bf16 v[48:63], v[64:67], v[80:83], v[48:63]
	ds_read_b64_tr_b16 v[80:81], v195 offset:0x400
	ds_read_b64_tr_b16 v[82:83], v195 offset:0xc00
	v_mfma_f32_32x32x16_bf16 v[48:63], v[68:71], v[84:87], v[48:63]
	ds_read_b64_tr_b16 v[84:85], v195 offset:0x1400
	ds_read_b64_tr_b16 v[86:87], v195 offset:0x1c00
	v_mfma_f32_32x32x16_bf16 v[48:63], v[72:75], v[88:91], v[48:63]
	ds_read_b64_tr_b16 v[88:89], v195 offset:0x2400
	ds_read_b64_tr_b16 v[90:91], v195 offset:0x2c00
	v_mfma_f32_32x32x16_bf16 v[48:63], v[76:79], v[92:95], v[48:63]
	ds_read_b64_tr_b16 v[92:93], v195 offset:0x3400
	ds_read_b64_tr_b16 v[94:95], v195 offset:0x3c00
	s_waitcnt lgkmcnt(0)
	v_mfma_f32_32x32x16_bf16 v[32:47], v[64:67], v[80:83], v[32:47]
	ds_read_b64_tr_b16 v[80:81], v195 offset:0x600
	ds_read_b64_tr_b16 v[82:83], v195 offset:0xe00
	v_mfma_f32_32x32x16_bf16 v[32:47], v[68:71], v[84:87], v[32:47]
	ds_read_b64_tr_b16 v[84:85], v195 offset:0x1600
	ds_read_b64_tr_b16 v[86:87], v195 offset:0x1e00
	v_mfma_f32_32x32x16_bf16 v[32:47], v[72:75], v[88:91], v[32:47]
	ds_read_b64_tr_b16 v[88:89], v195 offset:0x2600
	ds_read_b64_tr_b16 v[90:91], v195 offset:0x2e00
	v_mfma_f32_32x32x16_bf16 v[32:47], v[76:79], v[92:95], v[32:47]
	ds_read_b64_tr_b16 v[92:93], v195 offset:0x3600
	ds_read_b64_tr_b16 v[94:95], v195 offset:0x3e00
	s_waitcnt lgkmcnt(0)
	v_mfma_f32_32x32x16_bf16 v[16:31], v[64:67], v[80:83], v[16:31]
	s_xor_b32 s8, s15, 1
	s_lshl_b32 s9, s8, 14
	s_add_i32 s9, s9, 16
	v_add_u32_e32 v64, s9, v184
	s_lshl_b32 s8, s8, 13
	s_waitcnt vmcnt(0)
	s_waitcnt vmcnt(4)
	ds_write_b128 v64, v[156:159]
	v_mfma_f32_32x32x16_bf16 v[16:31], v[68:71], v[84:87], v[16:31]
	v_add_u32_e32 v64, s9, v186
	s_add_i32 s9, s9, s8
	s_waitcnt vmcnt(2)
	ds_write_b128 v64, v[160:163]
	v_add_u32_e32 v64, s9, v188
	ds_write_b128 v64, v[144:147] offset:32768
	s_waitcnt vmcnt(1)
	ds_write_b128 v64, v[152:155] offset:45056
	v_add_u32_e32 v64, s9, v189
	v_lshl_add_u64 v[166:167], v[166:167], 0, s[0:1]
	v_mfma_f32_32x32x16_bf16 v[16:31], v[72:75], v[88:91], v[16:31]
	v_lshl_add_u64 v[168:169], v[168:169], 0, s[18:19]
	s_cmpk_eq_i32 s14, 0x83
	s_waitcnt vmcnt(0)
	ds_write_b128 v64, v[148:151] offset:32768
	v_mov_b32_e32 v195, v176
	s_waitcnt lgkmcnt(0)
	s_barrier
	v_mfma_f32_32x32x16_bf16 v[16:31], v[76:79], v[92:95], v[16:31]
	s_cbranch_scc0 .LBB0_413

; #define SBAR() __builtin_amdgcn_sched_barrier(0)
; #define SLOAD(k0) do { vs0 = *(const bf16x8*)(vp0 + (long)(k0) * ldv); vs1 = *(const bf16x8*)(vp0 + (long)((k0) + 32) * ldv); \
;     ksg[0] = *(const bf16x8*)(kp0 + (long)(k0) * ldk0); \
;     if constexpr (DQK == 192) { ksg[1] = *(const bf16x8*)(kp0 + (long)((k0) + 32) * ldk0); ksg[2] = *(const bf16x8*)(kp2 + (long)(k0) * ldk1); } } while (0)
; DEVI void partialSM(f32x16& p0, f32x16& p1, float& m_reg, float& mn, float& alpha, float scale) {
;   const float C = scale * 1.4426950408889634f;
;   float pmax = p0[0];
; #pragma unroll
;   for (int r = 1; r < 16; ++r) pmax = fmaxf(pmax, p0[r]);
; #pragma unroll
;   for (int r = 0; r < 16; ++r) pmax = fmaxf(pmax, p1[r]);
;   { auto rr = __builtin_amdgcn_permlane32_swap(__float_as_uint(pmax), __float_as_uint(pmax), false, false);
;     pmax = fmaxf(__uint_as_float(rr[0]), __uint_as_float(rr[1])); }
;   if (__builtin_expect(__all(pmax - m_reg <= ATT_THR / scale), 1)) { mn = m_reg; alpha = 1.f; }
;   else { mn = fmaxf(m_reg, pmax); alpha = __builtin_amdgcn_exp2f((m_reg - mn) * C); m_reg = mn; }
;   const float mnC = -mn * C;
; #pragma unroll
;   for (int r = 0; r < 16; ++r) p0[r] = fmaf(p0[r], C, mnC);
; #pragma unroll
;   for (int r = 0; r < 16; ++r) p1[r] = fmaf(p1[r], C, mnC);
; #pragma unroll
;   for (int r = 0; r < 16; ++r) p0[r] = __builtin_amdgcn_exp2f(p0[r]);
; }
; template <int DQK, bool PIPE>
; DEVI void attn_body(const u16* __restrict__ Qb, int ldq, const u16* __restrict__ K0, int ldk0, const u16* __restrict__ K1, int ldk1,
;                     const u16* __restrict__ Vh, int ldv, u16* __restrict__ Ob, int ldo, int seq, float scale, char* lds) {
;     ...
;     for (int j = 1; j + 1 < NT; j += 2) {
;       SBAR(); QKT(pB0, pB1, K_lds + SHM_K);
;       finishSM(pA0, pA1, alA, l_reg, pa0, pa1, pa2, pa3); SBAR();
;       SLOAD((j + 1) * 64); SBAR();
;       pv_d0(o, vb0, pa0, pa1, pa2, pa3); partialSM(pB0, pB1, m_reg, mnB, alB, scale);
;       __syncthreads(); SWAIT(); SWRITE(0);
;       RESC(alB); __syncthreads();
;       SBAR(); QKT(pA0, pA1, K_lds);
;       finishSM(pB0, pB1, alB, l_reg, pa0, pa1, pa2, pa3); SBAR();
;       SLOAD((j + 2) * 64); SBAR();
;       pv_d0(o, vb0 + SHM_V, pa0, pa1, pa2, pa3); partialSM(pA0, pA1, m_reg, mnA, alA, scale);
;       __syncthreads(); SWAIT(); SWRITE(1);
;       RESC(alA); __syncthreads();
;     }
.LBB0_477:
	v_cndmask_b32_e64 v148, v130, v148, s[8:9]
	v_mul_f32_e32 v112, 0xbe38aa3b, v148
	v_mov_b32_e32 v113, v112
	v_fmamk_f32 v80, v80, 0x3e38aa3b, v112
	v_fmamk_f32 v81, v81, 0x3e38aa3b, v112
	v_fmamk_f32 v82, v82, 0x3e38aa3b, v112
	v_fmamk_f32 v83, v83, 0x3e38aa3b, v112
	v_fmamk_f32 v84, v84, 0x3e38aa3b, v112
	v_fmamk_f32 v85, v85, 0x3e38aa3b, v112
	v_fmamk_f32 v86, v86, 0x3e38aa3b, v112
	v_fmamk_f32 v87, v87, 0x3e38aa3b, v112
	v_fmamk_f32 v88, v88, 0x3e38aa3b, v112
	v_fmamk_f32 v89, v89, 0x3e38aa3b, v112
	v_fmamk_f32 v90, v90, 0x3e38aa3b, v112
	v_fmamk_f32 v91, v91, 0x3e38aa3b, v112
	v_fmamk_f32 v92, v92, 0x3e38aa3b, v112
	v_fmamk_f32 v93, v93, 0x3e38aa3b, v112
	v_fmamk_f32 v94, v94, 0x3e38aa3b, v112
	v_fmac_f32_e32 v113, 0x3e38aa3b, v95
	v_exp_f32_e32 v157, v80
	v_exp_f32_e32 v159, v81
	v_exp_f32_e32 v161, v82
	v_exp_f32_e32 v163, v83
	v_exp_f32_e32 v165, v84
	v_exp_f32_e32 v167, v85
	v_exp_f32_e32 v168, v86
	v_exp_f32_e32 v170, v87
	v_exp_f32_e32 v155, v88
	v_exp_f32_e32 v156, v89
	v_exp_f32_e32 v158, v90
	v_exp_f32_e32 v160, v91
	v_exp_f32_e32 v162, v92
	v_exp_f32_e32 v164, v93
	v_exp_f32_e32 v166, v94
	v_exp_f32_e32 v169, v113
	v_pk_fma_f32 v[132:133], v[64:65], s[20:21], v[112:113] op_sel_hi:[1,0,0]
	v_add_f32_e32 v64, v149, v150
	v_fmac_f32_e32 v64, v147, v137
	v_add_f32_e32 v137, v153, v154
	s_add_i32 s15, s15, 2
	v_pk_fma_f32 v[130:131], v[66:67], s[20:21], v[112:113] op_sel_hi:[1,0,0]
	v_pk_fma_f32 v[120:121], v[68:69], s[20:21], v[112:113] op_sel_hi:[1,0,0]
	v_pk_fma_f32 v[116:117], v[70:71], s[20:21], v[112:113] op_sel_hi:[1,0,0]
	v_pk_fma_f32 v[114:115], v[72:73], s[20:21], v[112:113] op_sel_hi:[1,0,0]
	v_pk_fma_f32 v[122:123], v[74:75], s[20:21], v[112:113] op_sel_hi:[1,0,0]
	v_pk_fma_f32 v[118:119], v[76:77], s[20:21], v[112:113] op_sel_hi:[1,0,0]
	v_pk_fma_f32 v[112:113], v[78:79], s[20:21], v[112:113] op_sel_hi:[1,0,0]
	v_fmac_f32_e32 v137, v64, v152
	v_lshl_add_u64 v[126:127], v[126:127], 0, s[22:23]
	s_cmpk_gt_u32 s15, 0x80
	v_lshl_add_u64 v[128:129], v[128:129], 0, s[22:23]
	v_mov_b32_e32 v147, v151
	s_waitcnt lgkmcnt(0)
	s_barrier
	s_cbranch_scc0 .LBB0_469
